# GEMM K-loop head labels aligned to 64 bytes (.p2align 6)
# speedup vs baseline: 1.0088x; 1.0088x over previous
; template <class Epi, class Sched, bool ALIGN_EPI = false, bool SP2 = false>
; __device__ __forceinline__ void gemm_phase(PG8_LAS unsigned char* lds, const Gemm g, const Sched& S, const Epi& E, const int wid_in) {
;     ...
;         const char* nA = has_next ? (const char*)g.A + (size_t)nxt.pm * tstep : cA; const char* nB = has_next ? (const char*)g.Bt + (size_t)nxt.pn * tstep : cB;
;         for (int t = 0; t < nt; t += 2) {
;             const bool last = (t == nt - 2);
;             const char* a1 = cA + (size_t)(t + 1) * kstep;
;             const char* a2 = last ? nA : cA + (size_t)(t + 2) * kstep; const char* b2 = last ? nB : cB + (size_t)(t + 2) * kstep;
;             const char* a3 = a2 + kstep; const char* b3 = b2 + kstep;
;     ...
;         for (int a = 0; a < 2; ++a)
; #pragma unroll
;             for (int b = 0; b < 2; ++b)
; #pragma unroll
;                 for (int m = 0; m < 4; ++m)
; #pragma unroll
;                     for (int n = 0; n < 2; ++n) acc[a][b][m][n] = (f32x4){0.f, 0.f, 0.f, 0.f};
.LBB0_132:
	s_ashr_i32 s19, s18, 31
	s_lshl_b64 s[20:21], s[18:19], 20
	s_add_u32 s20, s76, s20
	s_addc_u32 s21, s77, s21
	s_and_b64 s[22:23], s[0:1], exec
	s_cselect_b32 s19, s21, s5
	s_cselect_b32 s40, s20, s4
	s_ashr_i32 s17, s16, 31
	s_lshl_b64 s[22:23], s[16:17], 20
	s_add_u32 s22, s26, s22
	s_addc_u32 s23, s27, s23
	s_and_b64 s[24:25], s[0:1], exec
	s_cselect_b32 s17, s23, s7
	s_cselect_b32 s41, s22, s6
	s_add_u32 s4, s4, 0x80080
	s_addc_u32 s5, s5, 0
	s_add_u32 s42, s6, 0x100
	v_mov_b32_e32 v0, 0
	s_addc_u32 s43, s7, 0
	s_mov_b32 s44, -2
	v_mov_b32_e32 v1, v0
	v_mov_b32_e32 v2, v0
	v_mov_b32_e32 v3, v0
	v_mov_b32_e32 v4, v0
	v_mov_b32_e32 v5, v0
	v_mov_b32_e32 v6, v0
	v_mov_b32_e32 v7, v0
	v_mov_b32_e32 v16, v0
	v_mov_b32_e32 v17, v0
	v_mov_b32_e32 v18, v0
	v_mov_b32_e32 v19, v0
	v_mov_b32_e32 v20, v0
	v_mov_b32_e32 v21, v0
	v_mov_b32_e32 v22, v0
	v_mov_b32_e32 v23, v0
	v_mov_b32_e32 v32, v0
	v_mov_b32_e32 v33, v0
	v_mov_b32_e32 v34, v0
	v_mov_b32_e32 v35, v0
	v_mov_b32_e32 v36, v0
	v_mov_b32_e32 v37, v0
	v_mov_b32_e32 v38, v0
	v_mov_b32_e32 v39, v0
	v_mov_b32_e32 v48, v0
	v_mov_b32_e32 v49, v0
	v_mov_b32_e32 v50, v0
	v_mov_b32_e32 v51, v0
	v_mov_b32_e32 v52, v0
	v_mov_b32_e32 v53, v0
	v_mov_b32_e32 v54, v0
	v_mov_b32_e32 v55, v0
	v_mov_b32_e32 v8, v0
	v_mov_b32_e32 v9, v0
	v_mov_b32_e32 v10, v0
	v_mov_b32_e32 v11, v0
	v_mov_b32_e32 v12, v0
	v_mov_b32_e32 v13, v0
	v_mov_b32_e32 v14, v0
	v_mov_b32_e32 v15, v0
	v_mov_b32_e32 v24, v0
	v_mov_b32_e32 v25, v0
	v_mov_b32_e32 v26, v0
	v_mov_b32_e32 v27, v0
	v_mov_b32_e32 v28, v0
	v_mov_b32_e32 v29, v0
	v_mov_b32_e32 v30, v0
	v_mov_b32_e32 v31, v0
	v_mov_b32_e32 v40, v0
	v_mov_b32_e32 v41, v0
	v_mov_b32_e32 v42, v0
	v_mov_b32_e32 v43, v0
	v_mov_b32_e32 v44, v0
	v_mov_b32_e32 v45, v0
	v_mov_b32_e32 v46, v0
	v_mov_b32_e32 v47, v0
	v_mov_b32_e32 v56, v0
	v_mov_b32_e32 v57, v0
	v_mov_b32_e32 v58, v0
	v_mov_b32_e32 v59, v0
	v_mov_b32_e32 v60, v0
	v_mov_b32_e32 v61, v0
	v_mov_b32_e32 v62, v0
	v_mov_b32_e32 v63, v0
	v_mov_b32_e32 v64, v0
	v_mov_b32_e32 v65, v0
	v_mov_b32_e32 v66, v0
	v_mov_b32_e32 v67, v0
	v_mov_b32_e32 v68, v0
	v_mov_b32_e32 v69, v0
	v_mov_b32_e32 v70, v0
	v_mov_b32_e32 v71, v0
	v_mov_b32_e32 v80, v0
	v_mov_b32_e32 v81, v0
	v_mov_b32_e32 v82, v0
	v_mov_b32_e32 v83, v0
	v_mov_b32_e32 v84, v0
	v_mov_b32_e32 v85, v0
	v_mov_b32_e32 v86, v0
	v_mov_b32_e32 v87, v0
	v_mov_b32_e32 v96, v0
	v_mov_b32_e32 v97, v0
	v_mov_b32_e32 v98, v0
	v_mov_b32_e32 v99, v0
	v_mov_b32_e32 v100, v0
	v_mov_b32_e32 v101, v0
	v_mov_b32_e32 v102, v0
	v_mov_b32_e32 v103, v0
	v_mov_b32_e32 v112, v0
	v_mov_b32_e32 v113, v0
	v_mov_b32_e32 v114, v0
	v_mov_b32_e32 v115, v0
	v_mov_b32_e32 v116, v0
	v_mov_b32_e32 v117, v0
	v_mov_b32_e32 v118, v0
	v_mov_b32_e32 v119, v0
	v_mov_b32_e32 v72, v0
	v_mov_b32_e32 v73, v0
	v_mov_b32_e32 v74, v0
	v_mov_b32_e32 v75, v0
	v_mov_b32_e32 v76, v0
	v_mov_b32_e32 v77, v0
	v_mov_b32_e32 v78, v0
	v_mov_b32_e32 v79, v0
	v_mov_b32_e32 v88, v0
	v_mov_b32_e32 v89, v0
	v_mov_b32_e32 v90, v0
	v_mov_b32_e32 v91, v0
	v_mov_b32_e32 v92, v0
	v_mov_b32_e32 v93, v0
	v_mov_b32_e32 v94, v0
	v_mov_b32_e32 v95, v0
	v_mov_b32_e32 v104, v0
	v_mov_b32_e32 v105, v0
	v_mov_b32_e32 v106, v0
	v_mov_b32_e32 v107, v0
	v_mov_b32_e32 v108, v0
	v_mov_b32_e32 v109, v0
	v_mov_b32_e32 v110, v0
	v_mov_b32_e32 v111, v0
	v_mov_b32_e32 v120, v0
	v_mov_b32_e32 v121, v0
	v_mov_b32_e32 v122, v0
	v_mov_b32_e32 v123, v0
	v_mov_b32_e32 v124, v0
	v_mov_b32_e32 v125, v0
	v_mov_b32_e32 v126, v0
	v_mov_b32_e32 v127, v0
	.p2align	6

; template <class Epi, class Sched, bool ALIGN_EPI = false, bool SP2 = false>
; __device__ __forceinline__ void gemm_phase(PG8_LAS unsigned char* lds, const Gemm g, const Sched& S, const Epi& E, const int wid_in) {
;     ...
;         const char* nA = has_next ? (const char*)g.A + (size_t)nxt.pm * tstep : cA; const char* nB = has_next ? (const char*)g.Bt + (size_t)nxt.pn * tstep : cB;
;         for (int t = 0; t < nt; t += 2) {
;             const bool last = (t == nt - 2);
;             const char* a1 = cA + (size_t)(t + 1) * kstep;
;             const char* a2 = last ? nA : cA + (size_t)(t + 2) * kstep; const char* b2 = last ? nB : cB + (size_t)(t + 2) * kstep;
;             const char* a3 = a2 + kstep; const char* b3 = b2 + kstep;
;     ...
;         for (int a = 0; a < 2; ++a)
; #pragma unroll
;             for (int b = 0; b < 2; ++b)
; #pragma unroll
;                 for (int m = 0; m < 4; ++m)
; #pragma unroll
;                     for (int n = 0; n < 2; ++n) acc[a][b][m][n] = (f32x4){0.f, 0.f, 0.f, 0.f};
.LBB0_1098:
	s_ashr_i32 s19, s18, 31
	s_lshl_b64 s[20:21], s[18:19], 20
	s_add_u32 s20, s67, s20
	s_addc_u32 s21, s85, s21
	s_and_b64 s[22:23], s[6:7], exec
	s_cselect_b32 s19, s21, s5
	s_cselect_b32 s50, s20, s4
	s_ashr_i32 s17, s16, 31
	s_lshl_b64 s[22:23], s[16:17], 20
	s_add_u32 s22, s36, s22
	s_addc_u32 s23, s37, s23
	s_and_b64 s[26:27], s[6:7], exec
	s_cselect_b32 s17, s23, s25
	s_cselect_b32 s51, s22, s24
	s_add_u32 s52, s24, 0x100
	v_mov_b32_e32 v0, 0
	s_addc_u32 s53, s25, 0
	s_mov_b32 s54, -2
	s_waitcnt lgkmcnt(0)
	v_mov_b32_e32 v1, v0
	v_mov_b32_e32 v2, v0
	v_mov_b32_e32 v3, v0
	v_mov_b32_e32 v4, v0
	v_mov_b32_e32 v5, v0
	v_mov_b32_e32 v6, v0
	v_mov_b32_e32 v7, v0
	v_mov_b32_e32 v12, v0
	v_mov_b32_e32 v13, v0
	v_mov_b32_e32 v14, v0
	v_mov_b32_e32 v15, v0
	v_mov_b32_e32 v20, v0
	v_mov_b32_e32 v21, v0
	v_mov_b32_e32 v22, v0
	v_mov_b32_e32 v23, v0
	v_mov_b32_e32 v28, v0
	v_mov_b32_e32 v29, v0
	v_mov_b32_e32 v30, v0
	v_mov_b32_e32 v31, v0
	v_mov_b32_e32 v36, v0
	v_mov_b32_e32 v37, v0
	v_mov_b32_e32 v38, v0
	v_mov_b32_e32 v39, v0
	v_mov_b32_e32 v44, v0
	v_mov_b32_e32 v45, v0
	v_mov_b32_e32 v46, v0
	v_mov_b32_e32 v47, v0
	v_mov_b32_e32 v52, v0
	v_mov_b32_e32 v53, v0
	v_mov_b32_e32 v54, v0
	v_mov_b32_e32 v55, v0
	v_mov_b32_e32 v8, v0
	v_mov_b32_e32 v9, v0
	v_mov_b32_e32 v10, v0
	v_mov_b32_e32 v11, v0
	v_mov_b32_e32 v16, v0
	v_mov_b32_e32 v17, v0
	v_mov_b32_e32 v18, v0
	v_mov_b32_e32 v19, v0
	v_mov_b32_e32 v24, v0
	v_mov_b32_e32 v25, v0
	v_mov_b32_e32 v26, v0
	v_mov_b32_e32 v27, v0
	v_mov_b32_e32 v32, v0
	v_mov_b32_e32 v33, v0
	v_mov_b32_e32 v34, v0
	v_mov_b32_e32 v35, v0
	v_mov_b32_e32 v40, v0
	v_mov_b32_e32 v41, v0
	v_mov_b32_e32 v42, v0
	v_mov_b32_e32 v43, v0
	v_mov_b32_e32 v48, v0
	v_mov_b32_e32 v49, v0
	v_mov_b32_e32 v50, v0
	v_mov_b32_e32 v51, v0
	v_mov_b32_e32 v56, v0
	v_mov_b32_e32 v57, v0
	v_mov_b32_e32 v58, v0
	v_mov_b32_e32 v59, v0
	v_mov_b32_e32 v60, v0
	v_mov_b32_e32 v61, v0
	v_mov_b32_e32 v62, v0
	v_mov_b32_e32 v63, v0
	v_mov_b32_e32 v64, v0
	v_mov_b32_e32 v65, v0
	v_mov_b32_e32 v66, v0
	v_mov_b32_e32 v67, v0
	v_mov_b32_e32 v68, v0
	v_mov_b32_e32 v69, v0
	v_mov_b32_e32 v70, v0
	v_mov_b32_e32 v71, v0
	v_mov_b32_e32 v92, v0
	v_mov_b32_e32 v93, v0
	v_mov_b32_e32 v94, v0
	v_mov_b32_e32 v95, v0
	v_mov_b32_e32 v100, v0
	v_mov_b32_e32 v101, v0
	v_mov_b32_e32 v102, v0
	v_mov_b32_e32 v103, v0
	v_mov_b32_e32 v108, v0
	v_mov_b32_e32 v109, v0
	v_mov_b32_e32 v110, v0
	v_mov_b32_e32 v111, v0
	v_mov_b32_e32 v116, v0
	v_mov_b32_e32 v117, v0
	v_mov_b32_e32 v118, v0
	v_mov_b32_e32 v119, v0
	v_mov_b32_e32 v124, v0
	v_mov_b32_e32 v125, v0
	v_mov_b32_e32 v126, v0
	v_mov_b32_e32 v127, v0
	v_mov_b32_e32 v132, v0
	v_mov_b32_e32 v133, v0
	v_mov_b32_e32 v134, v0
	v_mov_b32_e32 v135, v0
	v_mov_b32_e32 v76, v0
	v_mov_b32_e32 v77, v0
	v_mov_b32_e32 v78, v0
	v_mov_b32_e32 v79, v0
	v_mov_b32_e32 v96, v0
	v_mov_b32_e32 v97, v0
	v_mov_b32_e32 v98, v0
	v_mov_b32_e32 v99, v0
	v_mov_b32_e32 v104, v0
	v_mov_b32_e32 v105, v0
	v_mov_b32_e32 v106, v0
	v_mov_b32_e32 v107, v0
	v_mov_b32_e32 v112, v0
	v_mov_b32_e32 v113, v0
	v_mov_b32_e32 v114, v0
	v_mov_b32_e32 v115, v0
	v_mov_b32_e32 v120, v0
	v_mov_b32_e32 v121, v0
	v_mov_b32_e32 v122, v0
	v_mov_b32_e32 v123, v0
	v_mov_b32_e32 v128, v0
	v_mov_b32_e32 v129, v0
	v_mov_b32_e32 v130, v0
	v_mov_b32_e32 v131, v0
	v_mov_b32_e32 v136, v0
	v_mov_b32_e32 v137, v0
	v_mov_b32_e32 v138, v0
	v_mov_b32_e32 v139, v0
	v_mov_b32_e32 v140, v0
	v_mov_b32_e32 v141, v0
	v_mov_b32_e32 v142, v0
	v_mov_b32_e32 v143, v0
	.p2align	6

; template <class Epi, class Sched, bool ALIGN_EPI = false, bool SP2 = false>
; __device__ __forceinline__ void gemm_phase(PG8_LAS unsigned char* lds, const Gemm g, const Sched& S, const Epi& E, const int wid_in) {
;     ...
;         const char* nA = has_next ? (const char*)g.A + (size_t)nxt.pm * tstep : cA; const char* nB = has_next ? (const char*)g.Bt + (size_t)nxt.pn * tstep : cB;
;         for (int t = 0; t < nt; t += 2) {
;             const bool last = (t == nt - 2);
;             const char* a1 = cA + (size_t)(t + 1) * kstep;
;             const char* a2 = last ? nA : cA + (size_t)(t + 2) * kstep; const char* b2 = last ? nB : cB + (size_t)(t + 2) * kstep;
;             const char* a3 = a2 + kstep; const char* b3 = b2 + kstep;
;     ...
;         for (int a = 0; a < 2; ++a)
; #pragma unroll
;             for (int b = 0; b < 2; ++b)
; #pragma unroll
;                 for (int m = 0; m < 4; ++m)
; #pragma unroll
;                     for (int n = 0; n < 2; ++n) acc[a][b][m][n] = (f32x4){0.f, 0.f, 0.f, 0.f};
.LBB0_1211:
	s_ashr_i32 s13, s12, 31
	s_lshl_b64 s[14:15], s[12:13], 20
	s_add_u32 s14, s76, s14
	s_addc_u32 s15, s77, s15
	s_and_b64 s[16:17], s[0:1], exec
	s_cselect_b32 s13, s15, s5
	s_cselect_b32 s43, s14, s4
	s_ashr_i32 s11, s10, 31
	s_lshl_b64 s[16:17], s[10:11], 20
	s_add_u32 s16, s23, s16
	s_addc_u32 s17, s24, s17
	s_and_b64 s[20:21], s[0:1], exec
	s_cselect_b32 s11, s17, s19
	s_cselect_b32 s44, s16, s18
	s_add_u32 s4, s4, 0x80080
	s_addc_u32 s5, s5, 0
	s_add_u32 s45, s18, 0x100
	v_mov_b32_e32 v0, 0
	s_addc_u32 s46, s19, 0
	s_mov_b32 s47, -2
	v_mov_b32_e32 v1, v0
	v_mov_b32_e32 v2, v0
	v_mov_b32_e32 v3, v0
	v_mov_b32_e32 v4, v0
	v_mov_b32_e32 v5, v0
	v_mov_b32_e32 v6, v0
	v_mov_b32_e32 v7, v0
	v_mov_b32_e32 v16, v0
	v_mov_b32_e32 v17, v0
	v_mov_b32_e32 v18, v0
	v_mov_b32_e32 v19, v0
	v_mov_b32_e32 v20, v0
	v_mov_b32_e32 v21, v0
	v_mov_b32_e32 v22, v0
	v_mov_b32_e32 v23, v0
	v_mov_b32_e32 v32, v0
	v_mov_b32_e32 v33, v0
	v_mov_b32_e32 v34, v0
	v_mov_b32_e32 v35, v0
	v_mov_b32_e32 v36, v0
	v_mov_b32_e32 v37, v0
	v_mov_b32_e32 v38, v0
	v_mov_b32_e32 v39, v0
	v_mov_b32_e32 v48, v0
	v_mov_b32_e32 v49, v0
	v_mov_b32_e32 v50, v0
	v_mov_b32_e32 v51, v0
	v_mov_b32_e32 v52, v0
	v_mov_b32_e32 v53, v0
	v_mov_b32_e32 v54, v0
	v_mov_b32_e32 v55, v0
	v_mov_b32_e32 v8, v0
	v_mov_b32_e32 v9, v0
	v_mov_b32_e32 v10, v0
	v_mov_b32_e32 v11, v0
	v_mov_b32_e32 v12, v0
	v_mov_b32_e32 v13, v0
	v_mov_b32_e32 v14, v0
	v_mov_b32_e32 v15, v0
	v_mov_b32_e32 v24, v0
	v_mov_b32_e32 v25, v0
	v_mov_b32_e32 v26, v0
	v_mov_b32_e32 v27, v0
	v_mov_b32_e32 v28, v0
	v_mov_b32_e32 v29, v0
	v_mov_b32_e32 v30, v0
	v_mov_b32_e32 v31, v0
	v_mov_b32_e32 v40, v0
	v_mov_b32_e32 v41, v0
	v_mov_b32_e32 v42, v0
	v_mov_b32_e32 v43, v0
	v_mov_b32_e32 v44, v0
	v_mov_b32_e32 v45, v0
	v_mov_b32_e32 v46, v0
	v_mov_b32_e32 v47, v0
	v_mov_b32_e32 v56, v0
	v_mov_b32_e32 v57, v0
	v_mov_b32_e32 v58, v0
	v_mov_b32_e32 v59, v0
	v_mov_b32_e32 v60, v0
	v_mov_b32_e32 v61, v0
	v_mov_b32_e32 v62, v0
	v_mov_b32_e32 v63, v0
	v_mov_b32_e32 v64, v0
	v_mov_b32_e32 v65, v0
	v_mov_b32_e32 v66, v0
	v_mov_b32_e32 v67, v0
	v_mov_b32_e32 v68, v0
	v_mov_b32_e32 v69, v0
	v_mov_b32_e32 v70, v0
	v_mov_b32_e32 v71, v0
	v_mov_b32_e32 v80, v0
	v_mov_b32_e32 v81, v0
	v_mov_b32_e32 v82, v0
	v_mov_b32_e32 v83, v0
	v_mov_b32_e32 v84, v0
	v_mov_b32_e32 v85, v0
	v_mov_b32_e32 v86, v0
	v_mov_b32_e32 v87, v0
	v_mov_b32_e32 v96, v0
	v_mov_b32_e32 v97, v0
	v_mov_b32_e32 v98, v0
	v_mov_b32_e32 v99, v0
	v_mov_b32_e32 v100, v0
	v_mov_b32_e32 v101, v0
	v_mov_b32_e32 v102, v0
	v_mov_b32_e32 v103, v0
	v_mov_b32_e32 v112, v0
	v_mov_b32_e32 v113, v0
	v_mov_b32_e32 v114, v0
	v_mov_b32_e32 v115, v0
	v_mov_b32_e32 v116, v0
	v_mov_b32_e32 v117, v0
	v_mov_b32_e32 v118, v0
	v_mov_b32_e32 v119, v0
	v_mov_b32_e32 v72, v0
	v_mov_b32_e32 v73, v0
	v_mov_b32_e32 v74, v0
	v_mov_b32_e32 v75, v0
	v_mov_b32_e32 v76, v0
	v_mov_b32_e32 v77, v0
	v_mov_b32_e32 v78, v0
	v_mov_b32_e32 v79, v0
	v_mov_b32_e32 v88, v0
	v_mov_b32_e32 v89, v0
	v_mov_b32_e32 v90, v0
	v_mov_b32_e32 v91, v0
	v_mov_b32_e32 v92, v0
	v_mov_b32_e32 v93, v0
	v_mov_b32_e32 v94, v0
	v_mov_b32_e32 v95, v0
	v_mov_b32_e32 v104, v0
	v_mov_b32_e32 v105, v0
	v_mov_b32_e32 v106, v0
	v_mov_b32_e32 v107, v0
	v_mov_b32_e32 v108, v0
	v_mov_b32_e32 v109, v0
	v_mov_b32_e32 v110, v0
	v_mov_b32_e32 v111, v0
	v_mov_b32_e32 v120, v0
	v_mov_b32_e32 v121, v0
	v_mov_b32_e32 v122, v0
	v_mov_b32_e32 v123, v0
	v_mov_b32_e32 v124, v0
	v_mov_b32_e32 v125, v0
	v_mov_b32_e32 v126, v0
	v_mov_b32_e32 v127, v0
	.p2align	6

; template <class Epi, class Sched, bool ALIGN_EPI = false, bool SP2 = false>
; __device__ __forceinline__ void gemm_phase(PG8_LAS unsigned char* lds, const Gemm g, const Sched& S, const Epi& E, const int wid_in) {
;     ...
;         const char* nA = has_next ? (const char*)g.A + (size_t)nxt.pm * tstep : cA; const char* nB = has_next ? (const char*)g.Bt + (size_t)nxt.pn * tstep : cB;
;         for (int t = 0; t < nt; t += 2) {
;             const bool last = (t == nt - 2);
;             const char* a1 = cA + (size_t)(t + 1) * kstep;
;             const char* a2 = last ? nA : cA + (size_t)(t + 2) * kstep; const char* b2 = last ? nB : cB + (size_t)(t + 2) * kstep;
;             const char* a3 = a2 + kstep; const char* b3 = b2 + kstep;
;     ...
;         for (int a = 0; a < 2; ++a)
; #pragma unroll
;             for (int b = 0; b < 2; ++b)
; #pragma unroll
;                 for (int m = 0; m < 4; ++m)
; #pragma unroll
;                     for (int n = 0; n < 2; ++n) acc[a][b][m][n] = (f32x4){0.f, 0.f, 0.f, 0.f};
.LBB0_1268:
	s_ashr_i32 s19, s18, 31
	s_lshl_b64 s[20:21], s[18:19], 22
	s_add_u32 s20, s78, s20
	s_addc_u32 s21, s79, s21
	s_and_b64 s[22:23], s[6:7], exec
	s_cselect_b32 s19, s21, s5
	s_cselect_b32 s49, s20, s4
	s_ashr_i32 s17, s16, 31
	s_lshl_b64 s[22:23], s[16:17], 22
	s_add_u32 s22, s37, s22
	s_addc_u32 s23, s38, s23
	s_and_b64 s[26:27], s[6:7], exec
	s_cselect_b32 s17, s23, s25
	s_cselect_b32 s50, s22, s24
	s_add_u32 s51, s24, 0x100
	v_mov_b32_e32 v0, 0
	s_addc_u32 s52, s25, 0
	s_mov_b32 s53, -2
	s_waitcnt lgkmcnt(0)
	v_mov_b32_e32 v1, v0
	v_mov_b32_e32 v2, v0
	v_mov_b32_e32 v3, v0
	v_mov_b32_e32 v4, v0
	v_mov_b32_e32 v5, v0
	v_mov_b32_e32 v6, v0
	v_mov_b32_e32 v7, v0
	v_mov_b32_e32 v12, v0
	v_mov_b32_e32 v13, v0
	v_mov_b32_e32 v14, v0
	v_mov_b32_e32 v15, v0
	v_mov_b32_e32 v16, v0
	v_mov_b32_e32 v17, v0
	v_mov_b32_e32 v18, v0
	v_mov_b32_e32 v19, v0
	v_mov_b32_e32 v28, v0
	v_mov_b32_e32 v29, v0
	v_mov_b32_e32 v30, v0
	v_mov_b32_e32 v31, v0
	v_mov_b32_e32 v36, v0
	v_mov_b32_e32 v37, v0
	v_mov_b32_e32 v38, v0
	v_mov_b32_e32 v39, v0
	v_mov_b32_e32 v44, v0
	v_mov_b32_e32 v45, v0
	v_mov_b32_e32 v46, v0
	v_mov_b32_e32 v47, v0
	v_mov_b32_e32 v52, v0
	v_mov_b32_e32 v53, v0
	v_mov_b32_e32 v54, v0
	v_mov_b32_e32 v55, v0
	v_mov_b32_e32 v8, v0
	v_mov_b32_e32 v9, v0
	v_mov_b32_e32 v10, v0
	v_mov_b32_e32 v11, v0
	v_mov_b32_e32 v20, v0
	v_mov_b32_e32 v21, v0
	v_mov_b32_e32 v22, v0
	v_mov_b32_e32 v23, v0
	v_mov_b32_e32 v24, v0
	v_mov_b32_e32 v25, v0
	v_mov_b32_e32 v26, v0
	v_mov_b32_e32 v27, v0
	v_mov_b32_e32 v32, v0
	v_mov_b32_e32 v33, v0
	v_mov_b32_e32 v34, v0
	v_mov_b32_e32 v35, v0
	v_mov_b32_e32 v40, v0
	v_mov_b32_e32 v41, v0
	v_mov_b32_e32 v42, v0
	v_mov_b32_e32 v43, v0
	v_mov_b32_e32 v48, v0
	v_mov_b32_e32 v49, v0
	v_mov_b32_e32 v50, v0
	v_mov_b32_e32 v51, v0
	v_mov_b32_e32 v56, v0
	v_mov_b32_e32 v57, v0
	v_mov_b32_e32 v58, v0
	v_mov_b32_e32 v59, v0
	v_mov_b32_e32 v60, v0
	v_mov_b32_e32 v61, v0
	v_mov_b32_e32 v62, v0
	v_mov_b32_e32 v63, v0
	v_mov_b32_e32 v64, v0
	v_mov_b32_e32 v65, v0
	v_mov_b32_e32 v66, v0
	v_mov_b32_e32 v67, v0
	v_mov_b32_e32 v68, v0
	v_mov_b32_e32 v69, v0
	v_mov_b32_e32 v70, v0
	v_mov_b32_e32 v71, v0
	v_mov_b32_e32 v92, v0
	v_mov_b32_e32 v93, v0
	v_mov_b32_e32 v94, v0
	v_mov_b32_e32 v95, v0
	v_mov_b32_e32 v100, v0
	v_mov_b32_e32 v101, v0
	v_mov_b32_e32 v102, v0
	v_mov_b32_e32 v103, v0
	v_mov_b32_e32 v108, v0
	v_mov_b32_e32 v109, v0
	v_mov_b32_e32 v110, v0
	v_mov_b32_e32 v111, v0
	v_mov_b32_e32 v116, v0
	v_mov_b32_e32 v117, v0
	v_mov_b32_e32 v118, v0
	v_mov_b32_e32 v119, v0
	v_mov_b32_e32 v124, v0
	v_mov_b32_e32 v125, v0
	v_mov_b32_e32 v126, v0
	v_mov_b32_e32 v127, v0
	v_mov_b32_e32 v132, v0
	v_mov_b32_e32 v133, v0
	v_mov_b32_e32 v134, v0
	v_mov_b32_e32 v135, v0
	v_mov_b32_e32 v76, v0
	v_mov_b32_e32 v77, v0
	v_mov_b32_e32 v78, v0
	v_mov_b32_e32 v79, v0
	v_mov_b32_e32 v96, v0
	v_mov_b32_e32 v97, v0
	v_mov_b32_e32 v98, v0
	v_mov_b32_e32 v99, v0
	v_mov_b32_e32 v104, v0
	v_mov_b32_e32 v105, v0
	v_mov_b32_e32 v106, v0
	v_mov_b32_e32 v107, v0
	v_mov_b32_e32 v112, v0
	v_mov_b32_e32 v113, v0
	v_mov_b32_e32 v114, v0
	v_mov_b32_e32 v115, v0
	v_mov_b32_e32 v120, v0
	v_mov_b32_e32 v121, v0
	v_mov_b32_e32 v122, v0
	v_mov_b32_e32 v123, v0
	v_mov_b32_e32 v128, v0
	v_mov_b32_e32 v129, v0
	v_mov_b32_e32 v130, v0
	v_mov_b32_e32 v131, v0
	v_mov_b32_e32 v136, v0
	v_mov_b32_e32 v137, v0
	v_mov_b32_e32 v138, v0
	v_mov_b32_e32 v139, v0
	v_mov_b32_e32 v140, v0
	v_mov_b32_e32 v141, v0
	v_mov_b32_e32 v142, v0
	v_mov_b32_e32 v143, v0
	.p2align	6
